# SEAM(5)/(6) grid barriers replaced by census-checked 4-workgroup panel barriers (same-XCD panel: no L2 write-back, L1 invalidate only)
# speedup vs baseline: 1.0168x; 1.0160x over previous
; #define LAS __attribute__((address_space(3)))
; __global__ void __launch_bounds__(512, 2) mk_fwd(Args args) {
;     ...
;     XcdBarrier bar = xcd_barrier_post((unsigned*)ws, (volatile LAS unsigned*)(lds + LDS_MISC));
;     ...
;     if (IN(0)) {
;         LAS float* scr = (LAS float*)(lds + wave * 16384);
;         const int gw = bid * 8 + wave, NGW = G * 8;
;         for (int it = gw; it < 16 * 192; it += NGW) {
;             const int kb = it / 192, j = it % 192, sg = j >> 5, seg = sg < 3 ? sg : sg + 1;
;             p0_transpose_kn(w_in, 1024, 10240, Wt_in, 0, scr, kb, seg * 32 + (j & 31), lane);
.LBB0_6:
	s_or_b64 exec, exec, s[4:5]
	s_and_saveexec_b64 s[4:5], s[92:93]
	s_getreg_b32 s0, hwreg(HW_REG_XCC_ID, 0, 4)
	s_and_b32 s0, s0, 7
	s_mul_i32 s0, s0, 3
	s_lshl_b32 s1, 1, s0
	s_and_b32 s0, s2, 63
	s_lshl_b32 s0, s0, 8
	s_add_u32 s0, s0, 0xc000
	v_mov_b32_e32 v0, s0
	v_mov_b32_e32 v1, s1
	global_atomic_add v0, v1, s[66:67]
	s_or_b64 exec, exec, s[4:5]
	s_add_u32 s74, s66, 0x100000
	s_addc_u32 s75, s67, 0
	s_cmp_lt_i32 s68, 1
	s_cselect_b64 s[0:1], -1, 0
	s_cmp_gt_i32 s69, 0
	s_cselect_b64 s[4:5], -1, 0
	v_lshrrev_b32_e32 v168, 6, v200
	s_and_b64 s[6:7], s[0:1], s[4:5]
	v_and_b32_e32 v170, 63, v200
	s_andn2_b64 vcc, exec, s[6:7]
	v_lshl_add_u32 v169, s2, 3, v168
	s_cbranch_vccnz .LBB0_14
	s_movk_i32 s0, 0xc00
	v_cmp_gt_i32_e32 vcc, s0, v169
	s_and_saveexec_b64 s[4:5], vcc
	s_cbranch_execz .LBB0_10
	v_and_b32_e32 v0, 31, v200
	v_readlane_b32 s8, v250, 1
	v_lshl_add_u32 v4, v168, 14, 0
	v_lshlrev_b32_e32 v2, 2, v0
	v_mov_b32_e32 v3, 0
	v_readlane_b32 s12, v250, 5
	v_readlane_b32 s13, v250, 6
	v_lshrrev_b32_e32 v5, 5, v170
	v_add_u32_e32 v6, v4, v2
	v_lshl_add_u64 v[0:1], s[12:13], 0, v[2:3]
	v_lshlrev_b32_e32 v2, 3, v200
	v_mul_u32_u24_e32 v7, 0x84, v5
	v_lshrrev_b32_e32 v10, 3, v170
	v_and_b32_e32 v2, 56, v2
	v_readlane_b32 s9, v250, 2
	v_readlane_b32 s10, v250, 3
	v_readlane_b32 s11, v250, 4
	v_readlane_b32 s14, v250, 7
	v_mul_u32_u24_e32 v8, 0x84, v2
	v_lshlrev_b32_e32 v2, 1, v2
	v_lshlrev_b32_e32 v9, 2, v10
	v_add_u32_e32 v16, v6, v7
	s_lshl_b32 s0, s70, 3
	v_lshl_add_u64 v[2:3], s[74:75], 0, v[2:3]
	v_add3_u32 v11, v4, v8, v9
	v_or_b32_e32 v12, 8, v10
	v_or_b32_e32 v13, 16, v10
	v_or_b32_e32 v14, 24, v10
	v_lshlrev_b32_e32 v15, 5, v169
	s_lshl_b32 s1, s70, 8
	s_mov_b64 s[8:9], 0
	s_mov_b32 s3, 0x2aaaaaab
	s_movk_i32 s10, 0xff40
	s_mov_b32 s11, 0xa000
	s_movk_i32 s12, 0x7fff
	s_mov_b32 s13, 0xffff0000
	s_movk_i32 s14, 0xbff
	v_add_u32_e32 v17, 0x400, v16
	v_add_u32_e32 v18, 0x800, v16
	v_add_u32_e32 v19, 0xc00, v16
	v_add_u32_e32 v20, 0x1000, v16
	v_add_u32_e32 v21, 0x1400, v16
	v_add_u32_e32 v22, 0x1800, v16
	v_add_u32_e32 v23, 0x1c00, v16
	v_mov_b32_e32 v4, v169
	v_readlane_b32 s15, v250, 8
	v_readlane_b32 s16, v250, 9
	v_readlane_b32 s17, v250, 10
	v_readlane_b32 s18, v250, 11
	v_readlane_b32 s19, v250, 12
	v_readlane_b32 s20, v250, 13
	v_readlane_b32 s21, v250, 14
	v_readlane_b32 s22, v250, 15
	v_readlane_b32 s23, v250, 16
	s_mov_b64 s[100:101], s[8:9]
	v_readfirstlane_b32 s98, v200
	s_nop 0
	s_lshr_b32 s98, s98, 6
	s_cmp_eq_u32 s98, 0
	s_cbranch_scc1 .Ldry_p0a_real
	s_mov_b64 exec, 0
	s_cmp_eq_u32 s98, 1
	s_cbranch_scc1 .Ldry_p0a_c1
	s_cmp_eq_u32 s98, 2
	s_cbranch_scc1 .Ldry_p0a_c2
	s_cmp_eq_u32 s98, 3
	s_cbranch_scc1 .Ldry_p0a_c3
	s_cmp_eq_u32 s98, 4
	s_cbranch_scc1 .Ldry_p0a_c4
	s_cmp_eq_u32 s98, 5
	s_cbranch_scc1 .Ldry_p0a_c5
	s_cmp_eq_u32 s98, 6
	s_cbranch_scc1 .Ldry_p0a_c6
	s_branch .Ldry_p0a_c7

; __device__ __forceinline__ unsigned xb_ld(unsigned* p)              { return __hip_atomic_load(p, __ATOMIC_RELAXED, __HIP_MEMORY_SCOPE_AGENT); }
; __device__ __forceinline__ unsigned xb_add(unsigned* p, unsigned v) { return __hip_atomic_fetch_add(p, v, __ATOMIC_RELAXED, __HIP_MEMORY_SCOPE_AGENT); }
; #define XB_SPIN(cond, bar) do { unsigned _sp = 0; while (cond) { __builtin_amdgcn_s_sleep(1); \
;     if ((++_sp & 255u) == 0u) { if (xb_ld(&(bar)[XB_TMO])) break; if (_sp > XB_SPIN_CAP) { atomicAdd(&(bar)[XB_TMO], 1u); break; } } } } while (0)
; #define SEAM(k) do { if (IN(k) && IN((k) + 1)) xcd_barrier(bar); } while (0)
; __device__ __forceinline__ void xcd_barrier(const XcdBarrier& b) {
;     asm volatile("s_waitcnt vmcnt(0)" ::: "memory");
;     __syncthreads();
;     if (threadIdx.x == 0) {
;         unsigned* bar = b.bar;
;         __builtin_amdgcn_s_waitcnt(0);
;         unsigned nloc = b.st[0], nx = b.st[1];
;         if (nloc == 0u) { xcd_barrier_complete(bar, b.x, nloc, nx); b.st[0] = nloc; b.st[1] = nx; }
;         const unsigned old = xb_add(&bar[XB_XSUB(b.x)], 1u);
;         const unsigned gen = old / nloc;
;         if (old + 1u == (gen + 1u) * nloc) {
;             __builtin_amdgcn_fence(__ATOMIC_RELEASE, "agent");
;             asm volatile("s_waitcnt vmcnt(0)" ::: "memory");
;             const unsigned og = xb_add(&bar[XB_TOP], 1u);
;             const unsigned tg = og / nx;
;             if (og + 1u == (tg + 1u) * nx) xb_add(&bar[XB_TOPGEN], 1u);
;             else XB_SPIN(xb_ld(&bar[XB_TOPGEN]) == tg, bar);
;             __builtin_amdgcn_fence(__ATOMIC_ACQUIRE, "agent");
;             xb_add(&bar[XB_XGEN(b.x)], 1u);
;             asm volatile("s_waitcnt vmcnt(0)" ::: "memory");
;         } else {
;             XB_SPIN(xb_ld(&bar[XB_XGEN(b.x)]) == gen, bar);
;             __builtin_amdgcn_fence(__ATOMIC_ACQUIRE, "agent");
;             asm volatile("s_waitcnt vmcnt(0)" ::: "memory");
;         }
;     }
;     __syncthreads();
; }
; __global__ void __launch_bounds__(512, 2) mk_fwd(Args args) {
;     ...
;     SEAM(5);
.LBB0_535:
	s_cmp_gt_i32 s69, 6
	s_cselect_b64 s[4:5], -1, 0
	s_and_b64 s[0:1], s[6:7], s[4:5]
	s_andn2_b64 vcc, exec, s[0:1]
	s_cbranch_vccnz .LBB0_589
	s_waitcnt vmcnt(0)
	s_waitcnt vmcnt(0)
	s_barrier
	s_and_saveexec_b64 s[6:7], s[92:93]
	s_cbranch_execz .LBB0_588
	s_and_b32 s0, s2, 63
	s_lshl_b32 s1, s0, 8
	v_mov_b32_e32 v1, 1
	s_add_u32 s1, s1, 0xc000
	v_mov_b32_e32 v3, s1
	global_load_dword v2, v3, s[66:67] sc1
	s_lshl_b32 s0, s0, 7
	s_add_u32 s0, s0, 0x8000
	v_mov_b32_e32 v0, s0
	s_getreg_b32 s8, hwreg(HW_REG_XCC_ID, 0, 4)
	s_and_b32 s8, s8, 7
	s_mul_i32 s8, s8, 3
	s_waitcnt vmcnt(0)
	v_readfirstlane_b32 s1, v2
	s_lshr_b32 s1, s1, s8
	s_and_b32 s1, s1, 7
	s_cmp_eq_u32 s1, 4
	s_cbranch_scc1 .Lpb5_fast
	buffer_wbl2 sc1
	s_waitcnt vmcnt(0)
.Lpb5_fast:
	global_atomic_add v0, v1, s[66:67]
	s_mov_b32 s1, 0
.Lpb5_spin:
	global_load_dword v2, v0, s[66:67] sc1
	s_waitcnt vmcnt(0)
	v_readfirstlane_b32 s8, v2
	s_cmp_ge_u32 s8, 4
	s_cbranch_scc1 .Lpb5_done
	s_sleep 1
	s_add_u32 s1, s1, 1
	s_cmp_lt_u32 s1, 0x80000
	s_cbranch_scc1 .Lpb5_spin
.Lpb5_done:
	buffer_inv sc1
	s_waitcnt vmcnt(0)
.LBB0_588:
	s_or_b64 exec, exec, s[6:7]
	s_waitcnt lgkmcnt(0)
	s_barrier

; __device__ __forceinline__ unsigned xb_ld(unsigned* p)              { return __hip_atomic_load(p, __ATOMIC_RELAXED, __HIP_MEMORY_SCOPE_AGENT); }
; __device__ __forceinline__ unsigned xb_add(unsigned* p, unsigned v) { return __hip_atomic_fetch_add(p, v, __ATOMIC_RELAXED, __HIP_MEMORY_SCOPE_AGENT); }
; #define XB_SPIN(cond, bar) do { unsigned _sp = 0; while (cond) { __builtin_amdgcn_s_sleep(1); \
;     if ((++_sp & 255u) == 0u) { if (xb_ld(&(bar)[XB_TMO])) break; if (_sp > XB_SPIN_CAP) { atomicAdd(&(bar)[XB_TMO], 1u); break; } } } } while (0)
; #define SEAM(k) do { if (IN(k) && IN((k) + 1)) xcd_barrier(bar); } while (0)
; __device__ __forceinline__ void xcd_barrier(const XcdBarrier& b) {
;     asm volatile("s_waitcnt vmcnt(0)" ::: "memory");
;     __syncthreads();
;     if (threadIdx.x == 0) {
;         unsigned* bar = b.bar;
;         __builtin_amdgcn_s_waitcnt(0);
;         unsigned nloc = b.st[0], nx = b.st[1];
;         if (nloc == 0u) { xcd_barrier_complete(bar, b.x, nloc, nx); b.st[0] = nloc; b.st[1] = nx; }
;         const unsigned old = xb_add(&bar[XB_XSUB(b.x)], 1u);
;         const unsigned gen = old / nloc;
;         if (old + 1u == (gen + 1u) * nloc) {
;             __builtin_amdgcn_fence(__ATOMIC_RELEASE, "agent");
;             asm volatile("s_waitcnt vmcnt(0)" ::: "memory");
;             const unsigned og = xb_add(&bar[XB_TOP], 1u);
;             const unsigned tg = og / nx;
;             if (og + 1u == (tg + 1u) * nx) xb_add(&bar[XB_TOPGEN], 1u);
;             else XB_SPIN(xb_ld(&bar[XB_TOPGEN]) == tg, bar);
;             __builtin_amdgcn_fence(__ATOMIC_ACQUIRE, "agent");
;             xb_add(&bar[XB_XGEN(b.x)], 1u);
;             asm volatile("s_waitcnt vmcnt(0)" ::: "memory");
;         } else {
;             XB_SPIN(xb_ld(&bar[XB_XGEN(b.x)]) == gen, bar);
;             __builtin_amdgcn_fence(__ATOMIC_ACQUIRE, "agent");
;             asm volatile("s_waitcnt vmcnt(0)" ::: "memory");
;         }
;     }
;     __syncthreads();
; }
; __global__ void __launch_bounds__(512, 2) mk_fwd(Args args) {
;     ...
;     SEAM(6);
.LBB0_696:
	s_cmp_gt_i32 s69, 7
	s_cselect_b64 s[4:5], -1, 0
	s_and_b64 s[0:1], s[8:9], s[4:5]
	s_andn2_b64 vcc, exec, s[0:1]
	s_cbranch_vccnz .LBB0_750
	s_waitcnt vmcnt(0)
	s_waitcnt vmcnt(0)
	s_barrier
	s_and_saveexec_b64 s[6:7], s[92:93]
	s_cbranch_execz .LBB0_749
	s_and_b32 s0, s2, 63
	s_lshl_b32 s1, s0, 8
	v_mov_b32_e32 v1, 1
	s_add_u32 s1, s1, 0xc000
	v_mov_b32_e32 v3, s1
	global_load_dword v2, v3, s[66:67] sc1
	s_lshl_b32 s0, s0, 7
	s_add_u32 s0, s0, 0xa000
	v_mov_b32_e32 v0, s0
	s_getreg_b32 s8, hwreg(HW_REG_XCC_ID, 0, 4)
	s_and_b32 s8, s8, 7
	s_mul_i32 s8, s8, 3
	s_waitcnt vmcnt(0)
	v_readfirstlane_b32 s1, v2
	s_lshr_b32 s1, s1, s8
	s_and_b32 s1, s1, 7
	s_cmp_eq_u32 s1, 4
	s_cbranch_scc1 .Lpb6_fast
	buffer_wbl2 sc1
	s_waitcnt vmcnt(0)

; __device__ __forceinline__ unsigned xb_ld(unsigned* p)              { return __hip_atomic_load(p, __ATOMIC_RELAXED, __HIP_MEMORY_SCOPE_AGENT); }
; #define XB_SPIN(cond, bar) do { unsigned _sp = 0; while (cond) { __builtin_amdgcn_s_sleep(1); \
;     if ((++_sp & 255u) == 0u) { if (xb_ld(&(bar)[XB_TMO])) break; if (_sp > XB_SPIN_CAP) { atomicAdd(&(bar)[XB_TMO], 1u); break; } } } } while (0)
; __device__ __forceinline__ void xcd_barrier(const XcdBarrier& b) {
;     ...
;             XB_SPIN(xb_ld(&bar[XB_XGEN(b.x)]) == gen, bar);
;             __builtin_amdgcn_fence(__ATOMIC_ACQUIRE, "agent");
;             asm volatile("s_waitcnt vmcnt(0)" ::: "memory");
;         }
;     }
;     __syncthreads();
.Lpb6_done:
	buffer_inv sc1
	s_waitcnt vmcnt(0)
.LBB0_749:
	s_or_b64 exec, exec, s[6:7]
	s_waitcnt lgkmcnt(0)
	s_barrier
